# work queues: first item of each workgroup is static (block id), later tickets offset by 256
# speedup vs baseline: 1.0222x; 1.0032x over previous
; DI unsigned xb_ld(unsigned* p)              { return __hip_atomic_load(p, __ATOMIC_RELAXED, __HIP_MEMORY_SCOPE_AGENT); }
; DI void xcd_barrier_complete(unsigned* bar, unsigned x, unsigned& nloc, unsigned& nx) {
;   const unsigned G = gridDim.x * gridDim.y * gridDim.z;
;   unsigned sum, cnt, mine, sp = 0u;
;   for (;;) {
;     sum = 0u; cnt = 0u; mine = 0u;
; #pragma unroll
;     for (unsigned j = 0; j < 16; ++j) { const unsigned c = xb_ld(&bar[XB_XCNT(j)]); sum += c; cnt += (c > 0u) ? 1u : 0u; mine = (j == x) ? c : mine; }
; DI void xcd_barrier(const XcdBarrier& b) {
;   asm volatile("s_waitcnt vmcnt(0)" ::: "memory");
;   __syncthreads();
;   if (threadIdx.x == 0) {
;     unsigned long long ba_ = (unsigned long long)b.bar; unsigned bx = b.x; asm volatile("" : "+v"(bx));
;     unsigned* bar = (unsigned*)ba_;
;     __builtin_amdgcn_s_waitcnt(0);
;     unsigned nloc = b.st[0], nx = b.st[1];
;     if (nloc == 0u) { xcd_barrier_complete(bar, bx, nloc, nx); b.st[0] = nloc; b.st[1] = nx; }
.LBB0_171:
	s_or_b64 exec, exec, s[0:1]
	s_waitcnt vmcnt(0)
	s_mov_b32 s100, 0
	s_barrier
	s_mov_b64 s[0:1], exec
	v_readlane_b32 s2, v249, 46
	v_readlane_b32 s3, v249, 47
	s_and_b64 s[2:3], s[0:1], s[2:3]
	s_mov_b64 exec, s[2:3]
	s_cbranch_execz .LBB0_219
	v_readlane_b32 s2, v249, 50
	s_nop 1
	v_mov_b32_e32 v1, s2
	s_add_i32 s2, 0, 0x23c00
	v_mov_b32_e32 v0, s2
	s_waitcnt vmcnt(0) expcnt(0) lgkmcnt(0)
	ds_read_b32 v0, v0
	s_add_i32 s2, 0, 0x23c04
	v_mov_b32_e32 v2, s2
	ds_read_b32 v5, v2
	s_waitcnt lgkmcnt(1)
	v_cmp_ne_u32_e32 vcc, 0, v0
	s_cbranch_vccnz .LBB0_187
	s_add_u32 s2, s54, 0x329d8800
	s_addc_u32 s3, s55, 0
	s_add_u32 s4, s54, 0x329d8a00
	s_addc_u32 s5, s55, 0
	s_add_u32 s6, s54, 0x329d8b00
	s_addc_u32 s7, s55, 0
	s_add_u32 s8, s54, 0x329d8c00
	s_addc_u32 s9, s55, 0
	s_add_u32 s10, s54, 0x329d8d00
	s_addc_u32 s11, s55, 0
	s_add_u32 s12, s54, 0x329d8e00
	s_addc_u32 s13, s55, 0
	s_add_u32 s14, s54, 0x329d8f00
	s_addc_u32 s15, s55, 0
	s_add_u32 s16, s54, 0x329d9000
	s_addc_u32 s17, s55, 0
	s_add_u32 s18, s54, 0x329d9100
	s_addc_u32 s19, s55, 0
	s_add_u32 s20, s54, 0x329d9200
	s_addc_u32 s21, s55, 0
	s_add_u32 s22, s54, 0x329d9300
	s_addc_u32 s23, s55, 0
	s_add_u32 s24, s54, 0x329d9400
	s_addc_u32 s25, s55, 0
	s_add_u32 s26, s54, 0x329d9500
	s_addc_u32 s27, s55, 0
	s_add_u32 s28, s54, 0x329d9600
	s_addc_u32 s29, s55, 0
	s_add_u32 s30, s54, 0x329d9700
	s_addc_u32 s31, s55, 0
	s_add_u32 s34, s54, 0x329d9800
	s_addc_u32 s35, s55, 0
	s_mul_i32 s44, s57, s33
	s_add_u32 s36, s54, 0x329d9900
	s_mul_i32 s44, s44, s56
	s_addc_u32 s37, s55, 0
	s_mov_b32 s45, 1
	v_mov_b32_e32 v17, 0
	s_branch .LBB0_175

;   DI void operator()(const AccT& acc, const Unit& u, int wr, int wc, int fr, int fq) const {
;     ...
;     for (int ai = 0; ai < 2; ++ai)
; #pragma unroll
;       for (int m = 0; m < 4; ++m) { float* rowp = C + (size_t)(u.pm * BM + ai * HALF + wr * 64 + m * 16 + fr) * 128 + wc * 32 + 4 * fq;
; #pragma unroll
;         for (int n = 0; n < 2; ++n) *(f32x4*)(rowp + n * 16) = acc[ai][0][m][n]; }
; DI void xcd_barrier(const XcdBarrier& b) {
;   asm volatile("s_waitcnt vmcnt(0)" ::: "memory");
;   __syncthreads();
;   if (threadIdx.x == 0) {
.LBB0_688:
	v_lshl_or_b32 v0, s1, 6, v67
	s_ashr_i32 s1, s0, 31
	s_lshl_b64 s[0:1], s[0:1], 22
	v_readlane_b32 s2, v250, 11
	v_readlane_b32 s3, v250, 12
	s_add_u32 s0, s2, s0
	s_addc_u32 s1, s3, s1
	s_lshl_b32 s2, s12, 2
	s_add_u32 s0, s0, s2
	v_lshl_add_u32 v68, s10, 8, v0
	s_addc_u32 s1, s1, 0
	v_mov_b32_e32 v67, v1
	v_ashrrev_i32_e32 v69, 31, v68
	v_lshl_add_u64 v[66:67], s[0:1], 0, v[66:67]
	v_lshlrev_b64 v[70:71], 9, v[68:69]
	v_lshl_add_u64 v[70:71], v[66:67], 0, v[70:71]
	global_store_dwordx4 v[70:71], v[42:45], off
	global_store_dwordx4 v[70:71], v[46:49], off offset:64
	s_mov_b64 s[0:1], 0x10000
	v_or_b32_e32 v42, 16, v68
	v_ashrrev_i32_e32 v43, 31, v42
	v_lshlrev_b64 v[42:43], 9, v[42:43]
	v_lshl_add_u64 v[42:43], v[66:67], 0, v[42:43]
	global_store_dwordx4 v[42:43], v[26:29], off
	global_store_dwordx4 v[42:43], v[30:33], off offset:64
	s_nop 0
	v_or_b32_e32 v26, 32, v68
	v_ashrrev_i32_e32 v27, 31, v26
	v_lshlrev_b64 v[26:27], 9, v[26:27]
	v_lshl_add_u64 v[26:27], v[66:67], 0, v[26:27]
	global_store_dwordx4 v[26:27], v[10:13], off
	global_store_dwordx4 v[26:27], v[18:21], off offset:64
	s_nop 0
	v_or_b32_e32 v10, 48, v68
	v_ashrrev_i32_e32 v11, 31, v10
	v_lshlrev_b64 v[10:11], 9, v[10:11]
	v_lshl_add_u64 v[10:11], v[66:67], 0, v[10:11]
	global_store_dwordx4 v[10:11], v[2:5], off
	global_store_dwordx4 v[10:11], v[6:9], off offset:64
	s_nop 0
	v_lshl_add_u64 v[2:3], v[70:71], 0, s[0:1]
	s_mov_b32 s0, 0x10000
	v_add_co_u32_e32 v4, vcc, s0, v70
	s_mov_b64 s[0:1], 0x12000
	s_nop 0
	v_addc_co_u32_e32 v5, vcc, 0, v71, vcc
	global_store_dwordx4 v[4:5], v[58:61], off
	global_store_dwordx4 v[2:3], v[62:65], off offset:64
	v_lshl_add_u64 v[2:3], v[70:71], 0, s[0:1]
	s_mov_b32 s0, 0x12000
	v_add_co_u32_e32 v4, vcc, s0, v70
	s_mov_b64 s[0:1], 0x14000
	s_nop 0
	v_addc_co_u32_e32 v5, vcc, 0, v71, vcc
	global_store_dwordx4 v[4:5], v[50:53], off
	global_store_dwordx4 v[2:3], v[54:57], off offset:64
	v_lshl_add_u64 v[2:3], v[70:71], 0, s[0:1]
	s_mov_b32 s0, 0x14000
	v_add_co_u32_e32 v4, vcc, s0, v70
	s_mov_b64 s[0:1], 0x16000
	s_nop 0
	v_addc_co_u32_e32 v5, vcc, 0, v71, vcc
	global_store_dwordx4 v[4:5], v[34:37], off
	global_store_dwordx4 v[2:3], v[38:41], off offset:64
	v_add_co_u32_e32 v4, vcc, 0x16000, v70
	v_lshl_add_u64 v[2:3], v[70:71], 0, s[0:1]
	s_nop 0
	v_addc_co_u32_e32 v5, vcc, 0, v71, vcc
	global_store_dwordx4 v[4:5], v[14:17], off
	global_store_dwordx4 v[2:3], v[22:25], off offset:64
	s_waitcnt vmcnt(0)
	s_barrier
	s_waitcnt vmcnt(0)
	s_waitcnt vmcnt(0)
	s_mov_b32 s100, 0
	s_barrier
	s_mov_b64 s[0:1], exec
	v_readlane_b32 s2, v249, 46
	v_readlane_b32 s3, v249, 47
	s_and_b64 s[2:3], s[0:1], s[2:3]
	s_mov_b64 exec, s[2:3]
	s_cbranch_execz .LBB0_736
	v_readlane_b32 s2, v249, 50
	s_nop 1
	v_mov_b32_e32 v0, s2
	v_readlane_b32 s2, v252, 24
	s_waitcnt vmcnt(0) expcnt(0) lgkmcnt(0)
	s_nop 0
	v_mov_b32_e32 v2, s2
	ds_read_b32 v2, v2
	v_readlane_b32 s2, v252, 25
	s_waitcnt lgkmcnt(0)
	v_cmp_ne_u32_e32 vcc, 0, v2
	v_mov_b32_e32 v3, s2
	ds_read_b32 v3, v3
	s_cbranch_vccnz .LBB0_704
	s_mov_b32 s8, 1
	s_branch .LBB0_692

; DI void xcd_barrier(const XcdBarrier& b) {
;   asm volatile("s_waitcnt vmcnt(0)" ::: "memory");
;   __syncthreads();
;   if (threadIdx.x == 0) {
;     unsigned long long ba_ = (unsigned long long)b.bar; unsigned bx = b.x; asm volatile("" : "+v"(bx));
;     unsigned* bar = (unsigned*)ba_;
;     __builtin_amdgcn_s_waitcnt(0);
;     unsigned nloc = b.st[0], nx = b.st[1];
;     if (nloc == 0u) { xcd_barrier_complete(bar, bx, nloc, nx); b.st[0] = nloc; b.st[1] = nx; }
.LBB0_754:
	s_or_b64 exec, exec, s[2:3]
	s_waitcnt vmcnt(0)
	s_mov_b32 s100, 0
	s_barrier
	s_mov_b64 s[0:1], exec
	v_readlane_b32 s2, v249, 46
	v_readlane_b32 s3, v249, 47
	s_and_b64 s[2:3], s[0:1], s[2:3]
	s_mov_b64 exec, s[2:3]
	s_cbranch_execz .LBB0_802
	v_readlane_b32 s2, v249, 50
	s_nop 1
	v_mov_b32_e32 v0, s2
	v_readlane_b32 s2, v252, 24
	s_waitcnt vmcnt(0) expcnt(0) lgkmcnt(0)
	s_nop 0
	v_mov_b32_e32 v2, s2
	ds_read_b32 v2, v2
	v_readlane_b32 s2, v252, 25
	s_waitcnt lgkmcnt(0)
	v_cmp_ne_u32_e32 vcc, 0, v2
	v_mov_b32_e32 v3, s2
	ds_read_b32 v3, v3
	s_cbranch_vccnz .LBB0_770
	s_mov_b32 s8, 1
	s_branch .LBB0_758

; DI int ltid() { int t = threadIdx.x; asm volatile("" : "+v"(t)); return t; }
; DI int fetch_item(unsigned* ctr0, int* slot) {
;   __syncthreads();
;   unsigned long long ca = (unsigned long long)ctr0; asm volatile("" : "+s"(ca));
;   unsigned* ctr = (unsigned*)ca;
;   if (ltid() == 0) *slot = (int)atomicAdd(ctr, 1u);
;   __syncthreads();
;   return *slot;
; DI void idxsel_phase(unsigned char* lds, const bf16_t* __restrict__ hbuf, const bf16_t* __restrict__ ikn, const float* __restrict__ iwf, u64* __restrict__ bits, unsigned* ctr) {
;     ...
;   for (;;) {
;     const int it = fetch_item(ctr, slot);
;     if (it >= 1024) break;
;     const int b = it & 1, jq = 511 - (it >> 1), t0 = b * SL + 8 * jq, ntile = (8 * jq + 8 + 31) >> 5;
;     { bf16x8 a[4][4]; f32x4 w[4][4];
; #pragma unroll
;       for (int u = 0; u < 4; ++u) {
;         const bf16_t* ap = hbuf + (size_t)(t0 + 2 * u + qi) * NPHYS + H_IQ + hd * 64 + kh * 8;
;         const float* wp = iwf + (size_t)(t0 + 2 * u + kh) * 16;
; #pragma unroll
;         for (int ks = 0; ks < 4; ++ks) { a[u][ks] = *(const bf16x8*)(ap + ks * 16); w[u][ks] = *(const f32x4*)(wp + 4 * ks); }
;       }
;       if (wid < ntile) {
;         const bf16_t* kp = ikn + (size_t)(b * SL + 32 * wid + i32) * 64 + kh * 8;
;         bf16x8 nb[4];
; #pragma unroll
;         for (int ks = 0; ks < 4; ++ks) nb[ks] = *(const bf16x8*)(kp + ks * 16);
.LBB0_940:
	v_readlane_b32 s2, v252, 43
	v_readlane_b32 s3, v252, 44
	v_mov_b32_e32 v0, v248
	s_barrier
	s_nop 0
	v_cmp_eq_u32_e32 vcc, 0, v0
	s_and_saveexec_b64 s[0:1], vcc
	s_cbranch_execz .LBB0_942
	v_mov_b64_e32 v[2:3], s[2:3]
	s_cmp_eq_u32 s100, 0
	s_cbranch_scc1 .Lfq0_static
	v_mov_b32_e32 v0, 1
	flat_atomic_add v0, v[2:3], v0 sc0
	s_waitcnt vmcnt(0) lgkmcnt(0)
	v_add_u32_e32 v0, 0x100, v0
	s_branch .Lfq0_join
.Lfq0_static:
	v_readlane_b32 s2, v252, 40
	s_nop 1
	v_mov_b32_e32 v0, s2
.Lfq0_join:
	v_readlane_b32 s2, v252, 26
	s_nop 1
	v_mov_b32_e32 v2, s2
	ds_write_b32 v2, v0
.LBB0_942:
	s_or_b64 exec, exec, s[0:1]
	s_mov_b32 s100, 1
	v_readlane_b32 s0, v252, 26
	s_waitcnt lgkmcnt(0)
	s_barrier
	v_mov_b32_e32 v0, s0
	ds_read_b32 v0, v0
	s_movk_i32 s0, 0x3ff
	s_waitcnt lgkmcnt(0)
	v_cmp_lt_i32_e32 vcc, s0, v0
	v_readfirstlane_b32 s2, v0
	s_mov_b64 s[0:1], -1
	s_cbranch_vccnz .LBB0_939
	s_lshl_b32 s1, s2, 2
	s_and_b32 s1, s1, -8
	s_lshl_b32 s0, s2, 12
	s_sub_i32 s8, 0xff8, s1
	s_sub_i32 s1, 0x1018, s1
	s_and_b32 s0, s0, 0x1000
	s_lshr_b32 s9, s1, 5
	s_add_i32 s72, s8, s0
	v_cmp_gt_i32_e32 vcc, s9, v193
	s_and_saveexec_b64 s[2:3], vcc
	s_cbranch_execz .LBB0_948
	v_or_b32_e32 v0, s72, v189
	s_or_b32 s1, s72, 2
	v_mad_i64_i32 v[2:3], s[4:5], v0, s33, v[182:183]
	v_or_b32_e32 v0, s1, v189
	s_or_b32 s6, s72, 4
	global_load_dwordx4 v[18:21], v[2:3], off offset:3072
	global_load_dwordx4 v[22:25], v[2:3], off offset:3104
	global_load_dwordx4 v[26:29], v[2:3], off offset:3136
	global_load_dwordx4 v[30:33], v[2:3], off offset:3168
	v_mad_i64_i32 v[2:3], s[4:5], v0, s33, v[182:183]
	v_or_b32_e32 v0, s6, v189
	s_or_b32 s7, s72, 6
	global_load_dwordx4 v[34:37], v[2:3], off offset:3072
	global_load_dwordx4 v[38:41], v[2:3], off offset:3104
	global_load_dwordx4 v[42:45], v[2:3], off offset:3136
	global_load_dwordx4 v[46:49], v[2:3], off offset:3168
	v_mad_i64_i32 v[2:3], s[4:5], v0, s33, v[182:183]
	v_or_b32_e32 v0, s7, v189
	global_load_dwordx4 v[50:53], v[2:3], off offset:3072
	global_load_dwordx4 v[54:57], v[2:3], off offset:3104
	global_load_dwordx4 v[58:61], v[2:3], off offset:3136
	global_load_dwordx4 v[62:65], v[2:3], off offset:3168
	v_mad_i64_i32 v[2:3], s[4:5], v0, s33, v[182:183]
	global_load_dwordx4 v[66:69], v[2:3], off offset:3072
	global_load_dwordx4 v[70:73], v[2:3], off offset:3104
	global_load_dwordx4 v[74:77], v[2:3], off offset:3136
	global_load_dwordx4 v[78:81], v[2:3], off offset:3168
	v_or_b32_e32 v2, s7, v188
	v_ashrrev_i32_e32 v3, 31, v2
	v_readlane_b32 s4, v250, 54
	v_lshlrev_b64 v[2:3], 6, v[2:3]
	v_readlane_b32 s5, v250, 55
	v_mov_b32_e32 v0, v192
	v_mov_b32_e32 v186, v193
	v_lshl_add_u64 v[2:3], s[4:5], 0, v[2:3]
	global_load_dwordx4 v[82:85], v[2:3], off
	global_load_dwordx4 v[86:89], v[2:3], off offset:16
	global_load_dwordx4 v[90:93], v[2:3], off offset:32
	global_load_dwordx4 v[94:97], v[2:3], off offset:48
	v_or_b32_e32 v2, s6, v188
	v_ashrrev_i32_e32 v3, 31, v2
	v_lshlrev_b64 v[2:3], 6, v[2:3]
	v_lshl_add_u64 v[2:3], s[4:5], 0, v[2:3]
	global_load_dwordx4 v[98:101], v[2:3], off
	global_load_dwordx4 v[102:105], v[2:3], off offset:16
	global_load_dwordx4 v[106:109], v[2:3], off offset:32
	global_load_dwordx4 v[110:113], v[2:3], off offset:48
	v_or_b32_e32 v2, s1, v188
	v_ashrrev_i32_e32 v3, 31, v2
	v_lshlrev_b64 v[2:3], 6, v[2:3]
	v_lshl_add_u64 v[2:3], s[4:5], 0, v[2:3]
	global_load_dwordx4 v[114:117], v[2:3], off
	global_load_dwordx4 v[118:121], v[2:3], off offset:16
	global_load_dwordx4 v[122:125], v[2:3], off offset:32
	global_load_dwordx4 v[126:129], v[2:3], off offset:48
	v_or_b32_e32 v2, s72, v188
	v_ashrrev_i32_e32 v3, 31, v2
	v_lshlrev_b64 v[2:3], 6, v[2:3]
	v_lshl_add_u64 v[2:3], s[4:5], 0, v[2:3]
	global_load_dwordx4 v[130:133], v[2:3], off
	global_load_dwordx4 v[134:137], v[2:3], off offset:16
	global_load_dwordx4 v[138:141], v[2:3], off offset:32
	global_load_dwordx4 v[142:145], v[2:3], off offset:48
	v_add_u32_e32 v2, s0, v190
	v_ashrrev_i32_e32 v3, 31, v2
	v_lshlrev_b64 v[2:3], 7, v[2:3]
	v_lshl_add_u64 v[184:185], v[178:179], 0, v[2:3]
	global_load_dwordx4 v[174:177], v[184:185], off
	global_load_dwordx4 v[170:173], v[184:185], off offset:32
	global_load_dwordx4 v[166:169], v[184:185], off offset:64
	global_load_dwordx4 v[146:149], v[184:185], off offset:96
	s_mov_b64 s[4:5], 0
	s_branch .LBB0_946

; DI void xcd_barrier(const XcdBarrier& b) {
;   asm volatile("s_waitcnt vmcnt(0)" ::: "memory");
;   __syncthreads();
;   if (threadIdx.x == 0) {
;     unsigned long long ba_ = (unsigned long long)b.bar; unsigned bx = b.x; asm volatile("" : "+v"(bx));
;     unsigned* bar = (unsigned*)ba_;
;     __builtin_amdgcn_s_waitcnt(0);
;     unsigned nloc = b.st[0], nx = b.st[1];
;     if (nloc == 0u) { xcd_barrier_complete(bar, bx, nloc, nx); b.st[0] = nloc; b.st[1] = nx; }
.LBB0_1106:
	s_waitcnt vmcnt(0)
	s_mov_b32 s100, 0
	s_barrier
	s_mov_b64 s[0:1], exec
	v_readlane_b32 s2, v249, 46
	v_readlane_b32 s3, v249, 47
	s_and_b64 s[2:3], s[0:1], s[2:3]
	v_readlane_b32 s85, v252, 40
	s_mov_b64 exec, s[2:3]
	s_cbranch_execz .LBB0_1154
	v_readlane_b32 s2, v249, 50
	s_nop 1
	v_mov_b32_e32 v0, s2
	v_readlane_b32 s2, v252, 24
	s_waitcnt vmcnt(0) expcnt(0) lgkmcnt(0)
	s_nop 0
	v_mov_b32_e32 v2, s2
	ds_read_b32 v2, v2
	v_readlane_b32 s2, v252, 25
	s_waitcnt lgkmcnt(0)
	v_cmp_ne_u32_e32 vcc, 0, v2
	v_mov_b32_e32 v3, s2
	ds_read_b32 v3, v3
	s_cbranch_vccnz .LBB0_1122
	s_mov_b32 s8, 1
	s_branch .LBB0_1110

; DI int ltid() { int t = threadIdx.x; asm volatile("" : "+v"(t)); return t; }
; DI int fetch_item(unsigned* ctr0, int* slot) {
;   __syncthreads();
;   unsigned long long ca = (unsigned long long)ctr0; asm volatile("" : "+s"(ca));
;   unsigned* ctr = (unsigned*)ca;
;   if (ltid() == 0) *slot = (int)atomicAdd(ctr, 1u);
;   __syncthreads();
;   return *slot;
; __global__ void __launch_bounds__(NTHR) fwd_megakernel(Params p) {
;     ...
;       for (;;) {
;         const int it = fetch_item(ctr + l * 4 + 1, slot);
;         if (it >= 256) break;
.LBB0_1157:
	s_mov_b64 s[4:5], s[6:7]
	v_mov_b32_e32 v0, v248
	s_barrier
	s_nop 0
	v_cmp_eq_u32_e32 vcc, 0, v0
	s_and_saveexec_b64 s[2:3], vcc
	s_cbranch_execz .LBB0_1159
	v_mov_b64_e32 v[2:3], s[4:5]
	s_cmp_eq_u32 s100, 0
	s_cbranch_scc1 .Lfq1_static
	v_mov_b32_e32 v0, 1
	flat_atomic_add v0, v[2:3], v0 sc0
	s_waitcnt vmcnt(0) lgkmcnt(0)
	v_add_u32_e32 v0, 0x100, v0
	s_branch .Lfq1_join
.Lfq1_static:
	v_readlane_b32 s4, v252, 40
	s_nop 1
	v_mov_b32_e32 v0, s4
.Lfq1_join:
	v_readlane_b32 s4, v252, 26
	s_nop 1
	v_mov_b32_e32 v2, s4
	ds_write_b32 v2, v0
.LBB0_1159:
	s_or_b64 exec, exec, s[2:3]
	s_mov_b32 s100, 1
	v_readlane_b32 s2, v252, 26
	s_waitcnt lgkmcnt(0)
	s_barrier
	v_mov_b32_e32 v0, s2
	ds_read_b32 v0, v0
	s_movk_i32 s2, 0xff
	s_waitcnt lgkmcnt(0)
	v_cmp_lt_i32_e32 vcc, s2, v0
	v_readfirstlane_b32 s4, v0
	s_mov_b64 s[2:3], -1
	s_cbranch_vccnz .LBB0_1156
	v_mov_b32_e32 v24, v248
	s_nop 0
	v_ashrrev_i32_e32 v26, 6, v24
	s_nop 0
	v_readfirstlane_b32 s2, v26
	s_cmp_gt_i32 s2, 3
	s_cselect_b64 s[8:9], -1, 0
	s_cmp_lt_i32 s2, 4
	s_cbranch_scc1 .LBB0_1162
	s_setprio 1

; DI void xcd_barrier(const XcdBarrier& b) {
;   asm volatile("s_waitcnt vmcnt(0)" ::: "memory");
;   __syncthreads();
;   if (threadIdx.x == 0) {
;     unsigned long long ba_ = (unsigned long long)b.bar; unsigned bx = b.x; asm volatile("" : "+v"(bx));
;     unsigned* bar = (unsigned*)ba_;
;     __builtin_amdgcn_s_waitcnt(0);
;     unsigned nloc = b.st[0], nx = b.st[1];
;     if (nloc == 0u) { xcd_barrier_complete(bar, bx, nloc, nx); b.st[0] = nloc; b.st[1] = nx; }
.LBB0_1213:
	s_waitcnt vmcnt(0)
	s_mov_b32 s100, 0
	s_barrier
	s_mov_b64 s[0:1], exec
	v_readlane_b32 s2, v249, 46
	v_readlane_b32 s3, v249, 47
	s_and_b64 s[2:3], s[0:1], s[2:3]
	s_mov_b64 exec, s[2:3]
	s_cbranch_execz .LBB0_1261
	v_readlane_b32 s2, v249, 50
	s_nop 1
	v_mov_b32_e32 v0, s2
	v_readlane_b32 s2, v252, 24
	s_waitcnt vmcnt(0) expcnt(0) lgkmcnt(0)
	s_nop 0
	v_mov_b32_e32 v2, s2
	ds_read_b32 v2, v2
	v_readlane_b32 s2, v252, 25
	s_waitcnt lgkmcnt(0)
	v_cmp_ne_u32_e32 vcc, 0, v2
	v_mov_b32_e32 v3, s2
	ds_read_b32 v3, v3
	s_cbranch_vccnz .LBB0_1229
	s_mov_b32 s8, 1
	s_branch .LBB0_1217

; DI void xcd_barrier(const XcdBarrier& b) {
;   asm volatile("s_waitcnt vmcnt(0)" ::: "memory");
;   __syncthreads();
;   if (threadIdx.x == 0) {
;     unsigned long long ba_ = (unsigned long long)b.bar; unsigned bx = b.x; asm volatile("" : "+v"(bx));
;     unsigned* bar = (unsigned*)ba_;
;     __builtin_amdgcn_s_waitcnt(0);
;     unsigned nloc = b.st[0], nx = b.st[1];
;     if (nloc == 0u) { xcd_barrier_complete(bar, bx, nloc, nx); b.st[0] = nloc; b.st[1] = nx; }
.LBB0_1282:
	v_readlane_b32 s0, v252, 51
	v_readlane_b32 s1, v252, 52
	s_or_b64 exec, exec, s[0:1]
	s_waitcnt vmcnt(0)
	s_mov_b32 s100, 0
	s_barrier
	s_mov_b64 s[0:1], exec
	v_readlane_b32 s2, v249, 46
	v_readlane_b32 s3, v249, 47
	s_and_b64 s[2:3], s[0:1], s[2:3]
	s_mov_b64 exec, s[2:3]
	s_cbranch_execz .LBB0_1330
	v_readlane_b32 s2, v249, 50
	s_nop 1
	v_mov_b32_e32 v0, s2
	v_readlane_b32 s2, v252, 24
	s_waitcnt vmcnt(0) expcnt(0) lgkmcnt(0)
	s_nop 0
	v_mov_b32_e32 v2, s2
	ds_read_b32 v2, v2
	v_readlane_b32 s2, v252, 25
	s_waitcnt lgkmcnt(0)
	v_cmp_ne_u32_e32 vcc, 0, v2
	v_mov_b32_e32 v3, s2
	ds_read_b32 v3, v3
	s_cbranch_vccnz .LBB0_1298
	s_mov_b32 s8, 1
	s_branch .LBB0_1286

; DI int ltid() { int t = threadIdx.x; asm volatile("" : "+v"(t)); return t; }
; DI int fetch_item(unsigned* ctr0, int* slot) {
;   __syncthreads();
;   unsigned long long ca = (unsigned long long)ctr0; asm volatile("" : "+s"(ca));
;   unsigned* ctr = (unsigned*)ca;
;   if (ltid() == 0) *slot = (int)atomicAdd(ctr, 1u);
;   __syncthreads();
;   return *slot;
.LBB0_1334:
	s_mov_b64 s[2:3], s[6:7]
	v_mov_b32_e32 v0, v248
	s_barrier
	s_nop 0
	v_cmp_eq_u32_e32 vcc, 0, v0
	s_and_saveexec_b64 s[0:1], vcc
	s_cbranch_execz .LBB0_1336
	v_mov_b64_e32 v[2:3], s[2:3]
	s_cmp_eq_u32 s100, 0
	s_cbranch_scc1 .Lfq2_static
	v_mov_b32_e32 v0, 1
	flat_atomic_add v0, v[2:3], v0 sc0
	s_waitcnt vmcnt(0) lgkmcnt(0)
	v_add_u32_e32 v0, 0x100, v0
	s_branch .Lfq2_join

; DI int ltid() { int t = threadIdx.x; asm volatile("" : "+v"(t)); return t; }
; DI int fetch_item(unsigned* ctr0, int* slot) {
;   __syncthreads();
;   unsigned long long ca = (unsigned long long)ctr0; asm volatile("" : "+s"(ca));
;   unsigned* ctr = (unsigned*)ca;
;   if (ltid() == 0) *slot = (int)atomicAdd(ctr, 1u);
;   __syncthreads();
;   return *slot;
; __global__ void __launch_bounds__(NTHR) fwd_megakernel(Params p) {
;     ...
;       for (;;) {
;         const int it = fetch_item(ctr + l * 4 + 2, slot);
;         if (it >= 1024) break;
;         f32x16 o[4]; float mo, lo;
;         const int r32 = lane & 31, hi = lane >> 5;
;         if (it >= 768) {
;           const int i2 = it - 768, qb = 15 - i2 / 16, r = i2 % 16, b = r >> 3, hh = r & 7, g = hh >> 2, rowg0 = b * SL + qb * 256;
;           const int jlo = 4 * qb - 8 > 0 ? 4 * qb - 8 : 0;
;           attn_core_skew<M_WINDOW>(ldsl, hbuf + (size_t)rowg0 * NPHYS + H_BQ + hh * 128, NPHYS, hbuf + (size_t)(b * SL) * NPHYS + H_BKV + (8 + g) * 128, NPHYS,
;                               (const bf16_t*)(ws + O_BVT) + (size_t)(((b * 2 + 1) * 2 + g) * 128) * SL, SL, qb * 256, jlo, 4 * qb + 4, nullptr, nullptr, o, mo, lo);
;           store_o_bf16(ldsl, (bf16_t*)(ws + O_OWIN), rowg0, hh * 128, o);
;           continue;
;         }
;         const int qb = 15 - it / 48, r = it % 48;
;         if (r < 16) {
;           f32x16 o8[8];
;           const int b = r >> 3, vh = r & 7, head = vh >> 1, mp = vh & 1, rowg0 = b * SL + qb * 256;
.LBB0_1336:
	s_or_b64 exec, exec, s[0:1]
	s_mov_b32 s100, 1
	v_readlane_b32 s0, v252, 26
	s_waitcnt lgkmcnt(0)
	s_barrier
	v_mov_b32_e32 v0, s0
	ds_read_b32 v0, v0
	s_movk_i32 s0, 0x3ff
	s_waitcnt lgkmcnt(0)
	v_cmp_lt_i32_e32 vcc, s0, v0
	v_readfirstlane_b32 s22, v0
	s_mov_b64 s[0:1], -1
	s_cbranch_vccnz .LBB0_1333
	s_cmpk_lt_i32 s22, 0x300
	s_cbranch_scc0 .LBB0_1446
	s_mul_hi_i32 s0, s22, 0xd5555555
	s_lshr_b32 s1, s0, 31
	s_ashr_i32 s24, s0, 3
	s_mul_hi_i32 s0, s22, 0x2aaaaaab
	s_add_i32 s24, s24, s1
	s_lshr_b32 s1, s0, 31
	s_lshr_b32 s0, s0, 3
	s_add_i32 s0, s0, s1
	s_mul_i32 s0, s0, 48
	s_add_i32 s25, s24, 15
	s_sub_i32 s23, s22, s0
	s_cmp_gt_i32 s23, 15
	s_mov_b64 s[0:1], -1
	s_cbranch_scc0 .LBB0_1414
	s_cmp_gt_u32 s23, 31
	s_cbranch_scc0 .LBB0_1404
	v_mov_b32_e32 v21, v248
	s_nop 0
	v_ashrrev_i32_e32 v0, 6, v21
	s_nop 0
	v_readfirstlane_b32 s0, v0
	s_cmp_gt_i32 s0, 3
	s_cselect_b64 s[4:5], -1, 0
	s_cmp_lt_i32 s0, 4
	s_cbranch_scc1 .LBB0_1342
	s_setprio 1

; DI void xcd_barrier(const XcdBarrier& b) {
;   asm volatile("s_waitcnt vmcnt(0)" ::: "memory");
;   __syncthreads();
;   if (threadIdx.x == 0) {
;     unsigned long long ba_ = (unsigned long long)b.bar; unsigned bx = b.x; asm volatile("" : "+v"(bx));
;     unsigned* bar = (unsigned*)ba_;
;     __builtin_amdgcn_s_waitcnt(0);
;     unsigned nloc = b.st[0], nx = b.st[1];
;     if (nloc == 0u) { xcd_barrier_complete(bar, bx, nloc, nx); b.st[0] = nloc; b.st[1] = nx; }
.LBB0_1607:
	s_mov_b32 s56, 0x800000
	s_or_b64 exec, exec, s[0:1]
	s_waitcnt vmcnt(0)
	s_mov_b32 s100, 0
	s_barrier
	s_mov_b64 s[0:1], exec
	v_readlane_b32 s2, v249, 46
	v_readlane_b32 s3, v249, 47
	s_and_b64 s[2:3], s[0:1], s[2:3]
	s_mov_b64 exec, s[2:3]
	s_cbranch_execz .LBB0_1655
	v_readlane_b32 s2, v249, 50
	s_nop 1
	v_mov_b32_e32 v0, s2
	v_readlane_b32 s2, v252, 24
	s_waitcnt vmcnt(0) expcnt(0) lgkmcnt(0)
	s_nop 0
	v_mov_b32_e32 v2, s2
	ds_read_b32 v2, v2
	v_readlane_b32 s2, v252, 25
	s_waitcnt lgkmcnt(0)
	v_cmp_ne_u32_e32 vcc, 0, v2
	v_mov_b32_e32 v3, s2
	ds_read_b32 v3, v3
	s_cbranch_vccnz .LBB0_1623
	s_mov_b32 s10, 1
	s_branch .LBB0_1611

; DI void xcd_barrier(const XcdBarrier& b) {
;   asm volatile("s_waitcnt vmcnt(0)" ::: "memory");
;   __syncthreads();
;   if (threadIdx.x == 0) {
;     unsigned long long ba_ = (unsigned long long)b.bar; unsigned bx = b.x; asm volatile("" : "+v"(bx));
;     unsigned* bar = (unsigned*)ba_;
;     __builtin_amdgcn_s_waitcnt(0);
;     unsigned nloc = b.st[0], nx = b.st[1];
;     if (nloc == 0u) { xcd_barrier_complete(bar, bx, nloc, nx); b.st[0] = nloc; b.st[1] = nx; }
.LBB0_1715:
	s_waitcnt vmcnt(0)
	s_mov_b32 s100, 0
	s_barrier
	s_mov_b64 s[0:1], exec
	v_readlane_b32 s2, v249, 46
	v_readlane_b32 s3, v249, 47
	s_and_b64 s[2:3], s[0:1], s[2:3]
	s_mov_b64 exec, s[2:3]
	s_cbranch_execz .LBB0_1763
	v_readlane_b32 s2, v249, 50
	s_nop 1
	v_mov_b32_e32 v0, s2
	v_readlane_b32 s2, v252, 24
	s_waitcnt vmcnt(0) expcnt(0) lgkmcnt(0)
	s_nop 0
	v_mov_b32_e32 v2, s2
	ds_read_b32 v2, v2
	v_readlane_b32 s2, v252, 25
	s_waitcnt lgkmcnt(0)
	v_cmp_ne_u32_e32 vcc, 0, v2
	v_mov_b32_e32 v3, s2
	ds_read_b32 v3, v3
	s_cbranch_vccnz .LBB0_1731
	s_mov_b32 s10, 1
	s_branch .LBB0_1719

; DI void xcd_barrier(const XcdBarrier& b) {
;   asm volatile("s_waitcnt vmcnt(0)" ::: "memory");
;   __syncthreads();
;   if (threadIdx.x == 0) {
;     unsigned long long ba_ = (unsigned long long)b.bar; unsigned bx = b.x; asm volatile("" : "+v"(bx));
;     unsigned* bar = (unsigned*)ba_;
;     __builtin_amdgcn_s_waitcnt(0);
;     unsigned nloc = b.st[0], nx = b.st[1];
;     if (nloc == 0u) { xcd_barrier_complete(bar, bx, nloc, nx); b.st[0] = nloc; b.st[1] = nx; }
.LBB0_1860:
	s_waitcnt vmcnt(0)
	s_mov_b32 s100, 0
	s_barrier
	s_mov_b64 s[0:1], exec
	v_readlane_b32 s2, v249, 46
	v_readlane_b32 s3, v249, 47
	v_readlane_b32 s48, v252, 34
	s_and_b64 s[2:3], s[0:1], s[2:3]
	v_readlane_b32 s49, v252, 35
	s_mov_b64 exec, s[2:3]
	s_cbranch_execz .LBB0_1908
	v_readlane_b32 s2, v249, 50
	s_nop 1
	v_mov_b32_e32 v0, s2
	v_readlane_b32 s2, v252, 24
	s_waitcnt vmcnt(0) expcnt(0) lgkmcnt(0)
	s_nop 0
	v_mov_b32_e32 v2, s2
	ds_read_b32 v2, v2
	v_readlane_b32 s2, v252, 25
	s_waitcnt lgkmcnt(0)
	v_cmp_ne_u32_e32 vcc, 0, v2
	v_mov_b32_e32 v3, s2
	ds_read_b32 v3, v3
	s_cbranch_vccnz .LBB0_1876
	s_mov_b32 s10, 1
	s_branch .LBB0_1864

; DI void xcd_barrier(const XcdBarrier& b) {
;   asm volatile("s_waitcnt vmcnt(0)" ::: "memory");
;   __syncthreads();
;   if (threadIdx.x == 0) {
;     unsigned long long ba_ = (unsigned long long)b.bar; unsigned bx = b.x; asm volatile("" : "+v"(bx));
;     unsigned* bar = (unsigned*)ba_;
;     __builtin_amdgcn_s_waitcnt(0);
;     unsigned nloc = b.st[0], nx = b.st[1];
;     if (nloc == 0u) { xcd_barrier_complete(bar, bx, nloc, nx); b.st[0] = nloc; b.st[1] = nx; }
.LBB0_1924:
	s_waitcnt vmcnt(0)
	s_waitcnt vmcnt(0)
	s_mov_b32 s100, 0
	s_barrier
	s_mov_b64 s[0:1], exec
	v_readlane_b32 s2, v249, 46
	v_readlane_b32 s3, v249, 47
	s_and_b64 s[2:3], s[0:1], s[2:3]
	s_mov_b64 exec, s[2:3]
	s_cbranch_execz .LBB0_1972
	v_readlane_b32 s2, v249, 50
	s_nop 1
	v_mov_b32_e32 v0, s2
	v_readlane_b32 s2, v252, 24
	s_waitcnt vmcnt(0) expcnt(0) lgkmcnt(0)
	s_nop 0
	v_mov_b32_e32 v2, s2
	ds_read_b32 v2, v2
	v_readlane_b32 s2, v252, 25
	s_waitcnt lgkmcnt(0)
	v_cmp_ne_u32_e32 vcc, 0, v2
	v_mov_b32_e32 v3, s2
	ds_read_b32 v3, v3
	s_cbranch_vccnz .LBB0_1940
	s_mov_b32 s10, 1
	s_branch .LBB0_1928

; DI void xcd_barrier(const XcdBarrier& b) {
;   asm volatile("s_waitcnt vmcnt(0)" ::: "memory");
;   __syncthreads();
;   if (threadIdx.x == 0) {
;     unsigned long long ba_ = (unsigned long long)b.bar; unsigned bx = b.x; asm volatile("" : "+v"(bx));
;     unsigned* bar = (unsigned*)ba_;
;     __builtin_amdgcn_s_waitcnt(0);
;     unsigned nloc = b.st[0], nx = b.st[1];
;     if (nloc == 0u) { xcd_barrier_complete(bar, bx, nloc, nx); b.st[0] = nloc; b.st[1] = nx; }
.LBB0_2196:
.LBB0_2238:
	s_waitcnt vmcnt(0)
	s_mov_b32 s100, 0
	s_barrier
	s_mov_b64 s[0:1], exec
	v_readlane_b32 s2, v249, 46
	v_readlane_b32 s3, v249, 47
	s_and_b64 s[2:3], s[0:1], s[2:3]
	s_mov_b64 exec, s[2:3]
	s_cbranch_execnz .LBB0_2239
	s_getpc_b64 s[98:99]

; __global__ void __launch_bounds__(NTHR) fwd_megakernel(Params p) {
	.amdhsa_kernel _Z14fwd_megakernel6Params
		.amdhsa_group_segment_fixed_size 0
		.amdhsa_private_segment_fixed_size 0
		.amdhsa_kernarg_size 416
		.amdhsa_user_sgpr_count 2
		.amdhsa_user_sgpr_dispatch_ptr 0
		.amdhsa_user_sgpr_queue_ptr 0
		.amdhsa_user_sgpr_kernarg_segment_ptr 1
		.amdhsa_user_sgpr_dispatch_id 0
		.amdhsa_user_sgpr_kernarg_preload_length 0
		.amdhsa_user_sgpr_kernarg_preload_offset 0
		.amdhsa_user_sgpr_private_segment_size 0
		.amdhsa_uses_dynamic_stack 0
		.amdhsa_enable_private_segment 0
		.amdhsa_system_sgpr_workgroup_id_x 1
		.amdhsa_system_sgpr_workgroup_id_y 0
		.amdhsa_system_sgpr_workgroup_id_z 0
		.amdhsa_system_sgpr_workgroup_info 0
		.amdhsa_system_vgpr_workitem_id 2
		.amdhsa_next_free_vgpr 256
		.amdhsa_next_free_sgpr 102
		.amdhsa_accum_offset 256
		.amdhsa_reserve_vcc 1
		.amdhsa_float_round_mode_32 0
		.amdhsa_float_round_mode_16_64 0
		.amdhsa_float_denorm_mode_32 3
		.amdhsa_float_denorm_mode_16_64 3
		.amdhsa_dx10_clamp 1
		.amdhsa_ieee_mode 1
		.amdhsa_fp16_overflow 0
		.amdhsa_tg_split 0
		.amdhsa_exception_fp_ieee_invalid_op 0
		.amdhsa_exception_fp_denorm_src 0
		.amdhsa_exception_fp_ieee_div_zero 0
		.amdhsa_exception_fp_ieee_overflow 0
		.amdhsa_exception_fp_ieee_underflow 0
		.amdhsa_exception_fp_ieee_inexact 0
		.amdhsa_exception_int_div_zero 0
	.end_amdhsa_kernel

; __global__ void __launch_bounds__(NTHR) fwd_megakernel(Params p) {
amdhsa.kernels:
  - .agpr_count:     0
    .args:
      - .offset:         0
        .size:           160
        .value_kind:     by_value
      - .offset:         160
        .size:           4
        .value_kind:     hidden_block_count_x
      - .offset:         164
        .size:           4
        .value_kind:     hidden_block_count_y
      - .offset:         168
        .size:           4
        .value_kind:     hidden_block_count_z
      - .offset:         172
        .size:           2
        .value_kind:     hidden_group_size_x
      - .offset:         174
        .size:           2
        .value_kind:     hidden_group_size_y
      - .offset:         176
        .size:           2
        .value_kind:     hidden_group_size_z
      - .offset:         178
        .size:           2
        .value_kind:     hidden_remainder_x
      - .offset:         180
        .size:           2
        .value_kind:     hidden_remainder_y
      - .offset:         182
        .size:           2
        .value_kind:     hidden_remainder_z
      - .offset:         200
        .size:           8
        .value_kind:     hidden_global_offset_x
      - .offset:         208
        .size:           8
        .value_kind:     hidden_global_offset_y
      - .offset:         216
        .size:           8
        .value_kind:     hidden_global_offset_z
      - .offset:         224
        .size:           2
        .value_kind:     hidden_grid_dims
      - .offset:         248
        .size:           8
        .value_kind:     hidden_multigrid_sync_arg
      - .offset:         280
        .size:           4
        .value_kind:     hidden_dynamic_lds_size
    .group_segment_fixed_size: 0
    .kernarg_segment_align: 8
    .kernarg_segment_size: 416
    .language:       OpenCL C
    .language_version:
      - 2
      - 0
    .max_flat_workgroup_size: 512
    .name:           _Z14fwd_megakernel6Params
    .private_segment_fixed_size: 0
    .sgpr_count:     108
    .sgpr_spill_count: 476
    .symbol:         _Z14fwd_megakernel6Params.kd
    .uniform_work_group_size: 1
    .uses_dynamic_stack: false
    .vgpr_count:     256
    .vgpr_spill_count: 0
    .wavefront_size: 64
